# depthwise-conv phase: the next-row loads of three of the four sub-steps of each sliding-window iteration are requested at the iteration top into spare registers and copied (under the original exec mas
# speedup vs baseline: 1.0120x; 1.0078x over previous
; __device__ __forceinline__ u32x4 pack8(const float* v) { u32x4 w; w.x = pk2(v[0], v[1]); w.y = pk2(v[2], v[3]); w.z = pk2(v[4], v[5]); w.w = pk2(v[6], v[7]); return w; }
; __device__ __forceinline__ void unpack8(u32x4 w, float* v) { v[0] = bflo(w.x); v[1] = bfhi(w.x); v[2] = bflo(w.y); v[3] = bfhi(w.y); v[4] = bflo(w.z); v[5] = bfhi(w.z); v[6] = bflo(w.w); v[7] = bfhi(w.w); }
; __device__ __forceinline__ float siluf_(float x) { return x / (1.f + __expf(-x)); }
; __global__ void __launch_bounds__(NTHR, 2) mk_fwd(Args args) {
;     ...
;                     u32x4 gc_ = *(const u32x4*)up, vc_ = *(const u32x4*)(up + FF);
; #pragma unroll 4
;                     for (int r = 0; r < 16; ++r) {
;                         u32x4 gn_ = (u32x4){0u, 0u, 0u, 0u}, vn_ = (u32x4){0u, 0u, 0u, 0u};
;                         const int ii = i0 + r;
;                         if (ii != LC - 1 && ii != TB - 1) { gn_ = *(const u32x4*)(up + (size_t)(r + 1) * FF2); vn_ = *(const u32x4*)(up + (size_t)(r + 1) * FF2 + FF); }
;                         float gm[8], gc[8], gn[8], vm[8], vc[8], vn[8], o[8];
;                         unpack8(gp_, gm); unpack8(gc_, gc); unpack8(gn_, gn); unpack8(vp_, vm); unpack8(vc_, vc); unpack8(vn_, vn);
; #pragma unroll
;                         for (int e = 0; e < 8; ++e) {
;                             const float a = wg0[e] * gm[e] + wg1[e] * gc[e] + wg2[e] * gn[e] + bg[e];
;                             const float v = wv0[e] * vm[e] + wv1[e] * vc[e] + wv2[e] * vn[e] + bv[e];
;                             o[e] = siluf_(a) * v;
;                         }
;                         *(u32x4*)(ACT + (size_t)(t0 + r) * FF + j0) = pack8(o);
.LBB0_91:
	v_lshl_add_u64 v[104:105], v[102:103], 0, v[42:43]
	v_add_co_u32_e32 v38, vcc, 0x89a2000, v104
	s_waitcnt vmcnt(0)
	v_lshlrev_b32_e32 v110, 16, v88
	v_addc_co_u32_e32 v39, vcc, 0, v105, vcc
	global_load_dwordx4 v[96:99], v[38:39], off offset:3072
	v_add_co_u32_e32 v38, vcc, 0x89a4000, v104
	v_and_b32_e32 v111, 0xffff0000, v88
	s_nop 0
	v_addc_co_u32_e32 v39, vcc, 0, v105, vcc
	global_load_dwordx4 v[92:95], v[38:39], off offset:512
	v_add_co_u32_e32 v140, vcc, 0x89a5000, v104
	s_nop 1
	v_addc_co_u32_e32 v141, vcc, 0, v105, vcc
	global_load_dwordx4 v[148:151], v[140:141], off offset:2048
	v_add_co_u32_e32 v142, vcc, 0x89a6000, v104
	s_nop 1
	v_addc_co_u32_e32 v143, vcc, 0, v105, vcc
	global_load_dwordx4 v[152:155], v[142:143], off offset:3584
	v_add_co_u32_e32 v144, vcc, 0x89a8000, v104
	s_nop 1
	v_addc_co_u32_e32 v145, vcc, 0, v105, vcc
	global_load_dwordx4 v[156:159], v[144:145], off offset:1024
	v_add_co_u32_e32 v146, vcc, 0x89a9000, v104
	s_nop 1
	v_addc_co_u32_e32 v147, vcc, 0, v105, vcc
	global_load_dwordx4 v[160:163], v[146:147], off offset:2560
	v_add_co_u32_e32 v172, vcc, 0x89ab000, v104
	s_nop 1
	v_addc_co_u32_e32 v173, vcc, 0, v105, vcc
	global_load_dwordx4 v[164:167], v[172:173], off
	v_add_co_u32_e32 v174, vcc, 0x89ac000, v104
	s_nop 1
	v_addc_co_u32_e32 v175, vcc, 0, v105, vcc
	global_load_dwordx4 v[168:171], v[174:175], off offset:1536
	v_lshlrev_b32_e32 v108, 16, v80
	v_and_b32_e32 v109, 0xffff0000, v80
	v_pk_mul_f32 v[116:117], v[32:33], v[110:111]
	v_lshlrev_b32_e32 v114, 16, v76
	v_pk_fma_f32 v[108:109], v[4:5], v[108:109], v[116:117]
	v_and_b32_e32 v115, 0xffff0000, v76
	v_lshlrev_b32_e32 v112, 16, v84
	v_and_b32_e32 v113, 0xffff0000, v84
	v_pk_mul_f32 v[118:119], v[60:61], v[112:113]
	v_lshlrev_b32_e32 v120, 16, v90
	v_pk_fma_f32 v[114:115], v[16:17], v[114:115], v[118:119]
	v_lshlrev_b32_e32 v118, 16, v85
	v_and_b32_e32 v119, 0xffff0000, v85
	v_and_b32_e32 v121, 0xffff0000, v90
	v_pk_mul_f32 v[124:125], v[52:53], v[120:121]
	v_lshlrev_b32_e32 v122, 16, v86
	v_and_b32_e32 v123, 0xffff0000, v86
	v_pk_mul_f32 v[126:127], v[68:69], v[122:123]
	s_waitcnt vmcnt(7)
	v_lshlrev_b32_e32 v38, 16, v96
	v_and_b32_e32 v39, 0xffff0000, v96
	v_pk_fma_f32 v[108:109], v[48:49], v[38:39], v[108:109]
	v_lshlrev_b32_e32 v96, 16, v77
	v_pk_add_f32 v[108:109], v[12:13], v[108:109]
	s_waitcnt vmcnt(6)
	v_lshlrev_b32_e32 v106, 16, v92
	v_mul_f32_e32 v37, 0xbfb8aa3b, v108
	v_exp_f32_e32 v116, v37
	v_mul_f32_e32 v37, 0xbfb8aa3b, v109
	v_exp_f32_e32 v117, v37
	v_and_b32_e32 v107, 0xffff0000, v92
	v_and_b32_e32 v85, 0xffff0000, v93
	v_pk_fma_f32 v[114:115], v[64:65], v[106:107], v[114:115]
	v_pk_add_f32 v[116:117], v[116:117], 1.0 op_sel_hi:[1,0]
	v_pk_add_f32 v[114:115], v[24:25], v[114:115]
	v_pk_mul_f32 v[128:129], v[60:61], v[106:107]
	v_rcp_f32_e32 v37, v117
	s_nop 0
	v_mul_f32_e32 v109, v109, v37
	v_and_b32_e32 v117, 0xffff0000, v89
	v_pk_fma_f32 v[112:113], v[16:17], v[112:113], v[128:129]
	v_rcp_f32_e32 v37, v116
	s_nop 0
	v_mul_f32_e32 v108, v108, v37
	v_lshlrev_b32_e32 v116, 16, v89
	v_lshlrev_b32_e32 v80, 16, v81
	v_and_b32_e32 v81, 0xffff0000, v81
	v_lshlrev_b32_e32 v88, 16, v97
	v_and_b32_e32 v89, 0xffff0000, v97
	v_and_b32_e32 v97, 0xffff0000, v77
	v_pk_mul_f32 v[76:77], v[34:35], v[116:117]
	v_lshlrev_b32_e32 v84, 16, v93
	v_pk_fma_f32 v[76:77], v[6:7], v[80:81], v[76:77]
	v_pk_mul_f32 v[80:81], v[62:63], v[118:119]
	v_pk_fma_f32 v[76:77], v[50:51], v[88:89], v[76:77]
	v_pk_fma_f32 v[80:81], v[18:19], v[96:97], v[80:81]
	v_pk_add_f32 v[76:77], v[14:15], v[76:77]
	v_pk_mul_f32 v[114:115], v[108:109], v[114:115]
	v_mul_f32_e32 v37, 0xbfb8aa3b, v76
	v_exp_f32_e32 v92, v37
	v_mul_f32_e32 v37, 0xbfb8aa3b, v77
	v_exp_f32_e32 v93, v37
	v_pk_fma_f32 v[80:81], v[66:67], v[84:85], v[80:81]
	v_pk_add_f32 v[92:93], v[92:93], 1.0 op_sel_hi:[1,0]
	s_nop 0
	v_pk_add_f32 v[80:81], v[26:27], v[80:81]
	v_rcp_f32_e32 v37, v93
	s_nop 0
	v_mul_f32_e32 v77, v77, v37
	v_and_b32_e32 v109, 0xffff0000, v94
	v_rcp_f32_e32 v37, v92
	s_nop 0
	v_mul_f32_e32 v76, v76, v37
	v_pk_mul_f32 v[76:77], v[76:77], v[80:81]
	v_lshlrev_b32_e32 v80, 16, v82
	v_and_b32_e32 v81, 0xffff0000, v82
	v_lshlrev_b32_e32 v96, 16, v98
	v_and_b32_e32 v97, 0xffff0000, v98
	v_pk_fma_f32 v[80:81], v[0:1], v[80:81], v[124:125]
	v_lshlrev_b32_e32 v92, 16, v78
	v_pk_fma_f32 v[80:81], v[56:57], v[96:97], v[80:81]
	v_and_b32_e32 v93, 0xffff0000, v78
	v_pk_add_f32 v[80:81], v[8:9], v[80:81]
	v_lshlrev_b32_e32 v108, 16, v94
	v_mul_f32_e32 v37, 0xbfb8aa3b, v80
	v_exp_f32_e32 v124, v37
	v_mul_f32_e32 v37, 0xbfb8aa3b, v81
	v_exp_f32_e32 v125, v37
	v_pk_fma_f32 v[92:93], v[20:21], v[92:93], v[126:127]
	v_lshlrev_b32_e32 v126, 16, v87
	v_pk_fma_f32 v[92:93], v[72:73], v[108:109], v[92:93]
	v_pk_add_f32 v[124:125], v[124:125], 1.0 op_sel_hi:[1,0]
	v_pk_add_f32 v[92:93], v[28:29], v[92:93]
	v_and_b32_e32 v127, 0xffff0000, v87
	v_and_b32_e32 v87, 0xffff0000, v95
	v_rcp_f32_e32 v37, v125
	s_nop 0
	v_mul_f32_e32 v81, v81, v37
	v_and_b32_e32 v125, 0xffff0000, v91
	v_rcp_f32_e32 v37, v124
	s_nop 0
	v_mul_f32_e32 v80, v80, v37
	v_lshlrev_b32_e32 v124, 16, v91
	v_pk_mul_f32 v[80:81], v[80:81], v[92:93]
	v_lshlrev_b32_e32 v82, 16, v83
	v_and_b32_e32 v83, 0xffff0000, v83
	v_pk_mul_f32 v[92:93], v[54:55], v[124:125]
	v_lshlrev_b32_e32 v90, 16, v99
	v_and_b32_e32 v91, 0xffff0000, v99
	v_pk_fma_f32 v[82:83], v[2:3], v[82:83], v[92:93]
	v_lshlrev_b32_e32 v78, 16, v79
	v_pk_fma_f32 v[82:83], v[58:59], v[90:91], v[82:83]
	v_and_b32_e32 v79, 0xffff0000, v79
	v_pk_add_f32 v[82:83], v[10:11], v[82:83]
	v_lshlrev_b32_e32 v86, 16, v95
	v_mul_f32_e32 v37, 0xbfb8aa3b, v82
	v_exp_f32_e32 v92, v37
	v_mul_f32_e32 v37, 0xbfb8aa3b, v83
	v_exp_f32_e32 v93, v37
	v_pk_mul_f32 v[94:95], v[70:71], v[126:127]
	v_cvt_pk_bf16_f32 v80, v80, v81
	v_pk_fma_f32 v[78:79], v[22:23], v[78:79], v[94:95]
	v_pk_add_f32 v[92:93], v[92:93], 1.0 op_sel_hi:[1,0]
	v_pk_fma_f32 v[78:79], v[74:75], v[86:87], v[78:79]
	v_pk_add_f32 v[78:79], v[30:31], v[78:79]
	v_rcp_f32_e32 v37, v93
	s_nop 0
	v_mul_f32_e32 v83, v83, v37
	s_mov_b32 s0, 0x13f20000
	v_rcp_f32_e32 v37, v92
	s_nop 0
	v_mul_f32_e32 v82, v82, v37
	v_lshl_add_u64 v[92:93], v[100:101], 0, v[42:43]
	v_pk_mul_f32 v[82:83], v[82:83], v[78:79]
	v_cvt_pk_bf16_f32 v79, v76, v77
	v_add_co_u32_e32 v76, vcc, s0, v92
	v_cvt_pk_bf16_f32 v78, v114, v115
	v_cvt_pk_bf16_f32 v81, v82, v83
	v_addc_co_u32_e32 v77, vcc, 0, v93, vcc
	s_mov_b32 s0, 0x89a5000
	global_store_dwordx4 v[76:77], v[78:81], off
	v_add_co_u32_e32 v76, vcc, s0, v104
	s_mov_b32 s0, 0x89a6000
	s_nop 0
	v_addc_co_u32_e32 v77, vcc, 0, v105, vcc
	s_nop 0
	v_add_co_u32_e32 v80, vcc, s0, v104
	v_pk_mul_f32 v[114:115], v[32:33], v[38:39]
	s_nop 0
	v_addc_co_u32_e32 v81, vcc, 0, v105, vcc
	s_nop 0
	v_pk_fma_f32 v[110:111], v[4:5], v[110:111], v[114:115]
	s_waitcnt vmcnt(6)
; __device__ __forceinline__ u32x4 pack8(const float* v) { u32x4 w; w.x = pk2(v[0], v[1]); w.y = pk2(v[2], v[3]); w.z = pk2(v[4], v[5]); w.w = pk2(v[6], v[7]); return w; }
; __device__ __forceinline__ void unpack8(u32x4 w, float* v) { v[0] = bflo(w.x); v[1] = bfhi(w.x); v[2] = bflo(w.y); v[3] = bfhi(w.y); v[4] = bflo(w.z); v[5] = bfhi(w.z); v[6] = bflo(w.w); v[7] = bfhi(w.w); }
; __device__ __forceinline__ float siluf_(float x) { return x / (1.f + __expf(-x)); }
; __global__ void __launch_bounds__(NTHR, 2) mk_fwd(Args args) {
;     ...
;                     for (int r = 0; r < 16; ++r) {
;                         u32x4 gn_ = (u32x4){0u, 0u, 0u, 0u}, vn_ = (u32x4){0u, 0u, 0u, 0u};
;                         const int ii = i0 + r;
;                         if (ii != LC - 1 && ii != TB - 1) { gn_ = *(const u32x4*)(up + (size_t)(r + 1) * FF2); vn_ = *(const u32x4*)(up + (size_t)(r + 1) * FF2 + FF); }
;                         float gm[8], gc[8], gn[8], vm[8], vc[8], vn[8], o[8];
;                         unpack8(gp_, gm); unpack8(gc_, gc); unpack8(gn_, gn); unpack8(vp_, vm); unpack8(vc_, vc); unpack8(vn_, vn);
; #pragma unroll
;                         for (int e = 0; e < 8; ++e) {
;                             const float a = wg0[e] * gm[e] + wg1[e] * gc[e] + wg2[e] * gn[e] + bg[e];
;                             const float v = wv0[e] * vm[e] + wv1[e] * vc[e] + wv2[e] * vn[e] + bv[e];
;                             o[e] = siluf_(a) * v;
;                         }
;                         *(u32x4*)(ACT + (size_t)(t0 + r) * FF + j0) = pack8(o);
	v_mov_b32_e32 v76, v148
	v_mov_b32_e32 v77, v149
	v_mov_b32_e32 v78, v150
	v_mov_b32_e32 v79, v151
	v_lshlrev_b32_e32 v98, 16, v76
	v_and_b32_e32 v99, 0xffff0000, v76
	v_pk_fma_f32 v[110:111], v[48:49], v[98:99], v[110:111]
	s_waitcnt vmcnt(5)
	v_mov_b32_e32 v80, v152
	v_mov_b32_e32 v81, v153
	v_mov_b32_e32 v82, v154
	v_mov_b32_e32 v83, v155
	v_lshlrev_b32_e32 v94, 16, v80
	v_pk_add_f32 v[110:111], v[12:13], v[110:111]
	v_and_b32_e32 v95, 0xffff0000, v80
	v_mul_f32_e32 v37, 0xbfb8aa3b, v110
	v_exp_f32_e32 v114, v37
	v_mul_f32_e32 v37, 0xbfb8aa3b, v111
	v_exp_f32_e32 v115, v37
	v_pk_fma_f32 v[112:113], v[64:65], v[94:95], v[112:113]
	v_pk_add_f32 v[114:115], v[114:115], 1.0 op_sel_hi:[1,0]
	s_nop 0
	v_pk_add_f32 v[112:113], v[24:25], v[112:113]
	v_rcp_f32_e32 v37, v115
	s_nop 0
	v_mul_f32_e32 v111, v111, v37
	s_nop 0
	v_rcp_f32_e32 v37, v114
	s_nop 0
	v_mul_f32_e32 v110, v110, v37
	v_pk_mul_f32 v[128:129], v[110:111], v[112:113]
	v_lshlrev_b32_e32 v112, 16, v77
	v_and_b32_e32 v113, 0xffff0000, v77
	v_pk_mul_f32 v[76:77], v[34:35], v[88:89]
	v_lshlrev_b32_e32 v110, 16, v81
	v_pk_fma_f32 v[76:77], v[6:7], v[116:117], v[76:77]
	v_and_b32_e32 v111, 0xffff0000, v81
	v_pk_fma_f32 v[76:77], v[50:51], v[112:113], v[76:77]
	v_pk_mul_f32 v[114:115], v[62:63], v[84:85]
	v_pk_add_f32 v[76:77], v[14:15], v[76:77]
	v_pk_fma_f32 v[114:115], v[18:19], v[118:119], v[114:115]
	v_mul_f32_e32 v37, 0xbfb8aa3b, v76
	v_exp_f32_e32 v80, v37
	v_mul_f32_e32 v37, 0xbfb8aa3b, v77
	v_exp_f32_e32 v81, v37
	v_pk_fma_f32 v[114:115], v[66:67], v[110:111], v[114:115]
	v_pk_add_f32 v[80:81], v[80:81], 1.0 op_sel_hi:[1,0]
	s_nop 0
	v_pk_add_f32 v[114:115], v[26:27], v[114:115]
	v_rcp_f32_e32 v37, v81
	s_nop 0
	v_mul_f32_e32 v77, v77, v37
	s_nop 0
	v_rcp_f32_e32 v37, v80
	s_nop 0
	v_mul_f32_e32 v76, v76, v37
	v_pk_mul_f32 v[80:81], v[52:53], v[96:97]
	v_lshlrev_b32_e32 v116, 16, v78
	v_and_b32_e32 v117, 0xffff0000, v78
	v_pk_fma_f32 v[80:81], v[0:1], v[120:121], v[80:81]
	v_pk_mul_f32 v[76:77], v[76:77], v[114:115]
	v_pk_fma_f32 v[80:81], v[56:57], v[116:117], v[80:81]
	v_lshlrev_b32_e32 v114, 16, v82
	v_pk_add_f32 v[80:81], v[8:9], v[80:81]
	v_and_b32_e32 v115, 0xffff0000, v82
	v_mul_f32_e32 v37, 0xbfb8aa3b, v80
	v_exp_f32_e32 v118, v37
	v_mul_f32_e32 v37, 0xbfb8aa3b, v81
	v_exp_f32_e32 v119, v37
	v_pk_mul_f32 v[120:121], v[68:69], v[108:109]
	v_pk_add_f32 v[118:119], v[118:119], 1.0 op_sel_hi:[1,0]
	s_nop 0
	v_pk_fma_f32 v[120:121], v[20:21], v[122:123], v[120:121]
	v_rcp_f32_e32 v37, v119
	s_nop 0
	v_mul_f32_e32 v81, v81, v37
	v_pk_fma_f32 v[120:121], v[72:73], v[114:115], v[120:121]
	v_pk_add_f32 v[120:121], v[28:29], v[120:121]
	v_rcp_f32_e32 v37, v118
	s_nop 0
	v_mul_f32_e32 v80, v80, v37
	v_pk_mul_f32 v[80:81], v[80:81], v[120:121]
	v_lshlrev_b32_e32 v120, 16, v79
	v_and_b32_e32 v121, 0xffff0000, v79
	v_pk_mul_f32 v[78:79], v[54:55], v[90:91]
	v_lshlrev_b32_e32 v118, 16, v83
	v_pk_fma_f32 v[78:79], v[2:3], v[124:125], v[78:79]
	v_and_b32_e32 v119, 0xffff0000, v83
	v_pk_fma_f32 v[78:79], v[58:59], v[120:121], v[78:79]
	v_pk_mul_f32 v[122:123], v[70:71], v[86:87]
	v_pk_add_f32 v[78:79], v[10:11], v[78:79]
	v_pk_fma_f32 v[122:123], v[22:23], v[126:127], v[122:123]
	v_mul_f32_e32 v37, 0xbfb8aa3b, v78
	v_exp_f32_e32 v82, v37
	v_mul_f32_e32 v37, 0xbfb8aa3b, v79
	v_exp_f32_e32 v83, v37
	v_pk_fma_f32 v[122:123], v[74:75], v[118:119], v[122:123]
	v_cvt_pk_bf16_f32 v80, v80, v81
	v_pk_add_f32 v[122:123], v[30:31], v[122:123]
	v_pk_add_f32 v[82:83], v[82:83], 1.0 op_sel_hi:[1,0]
	s_nop 0
	s_nop 0
	v_rcp_f32_e32 v37, v83
	s_nop 0
	v_mul_f32_e32 v79, v79, v37
	s_mov_b32 s0, 0x13f21000
	v_rcp_f32_e32 v37, v82
	s_nop 0
	v_mul_f32_e32 v78, v78, v37
	v_pk_mul_f32 v[82:83], v[78:79], v[122:123]
	v_cvt_pk_bf16_f32 v79, v76, v77
	v_add_co_u32_e32 v76, vcc, s0, v92
	v_cvt_pk_bf16_f32 v78, v128, v129
	v_cvt_pk_bf16_f32 v81, v82, v83
	v_addc_co_u32_e32 v77, vcc, 0, v93, vcc
	s_mov_b32 s0, 0x89a8000
	global_store_dwordx4 v[76:77], v[78:81], off offset:1536
	v_add_co_u32_e32 v76, vcc, s0, v104
	s_mov_b32 s0, 0x89a9000
	s_nop 0
	v_addc_co_u32_e32 v77, vcc, 0, v105, vcc
	s_nop 0
	v_add_co_u32_e32 v76, vcc, s0, v104
	v_pk_mul_f32 v[126:127], v[32:33], v[98:99]
	s_nop 0
	v_addc_co_u32_e32 v77, vcc, 0, v105, vcc
	s_nop 0
	v_pk_fma_f32 v[38:39], v[4:5], v[38:39], v[126:127]
	v_pk_mul_f32 v[128:129], v[60:61], v[94:95]
	s_waitcnt vmcnt(5)
	v_mov_b32_e32 v80, v156
	v_mov_b32_e32 v81, v157
	v_mov_b32_e32 v82, v158
	v_mov_b32_e32 v83, v159
	v_lshlrev_b32_e32 v124, 16, v80
	v_and_b32_e32 v125, 0xffff0000, v80
	v_pk_fma_f32 v[38:39], v[48:49], v[124:125], v[38:39]
	v_pk_fma_f32 v[106:107], v[16:17], v[106:107], v[128:129]
	v_pk_add_f32 v[38:39], v[12:13], v[38:39]
	s_waitcnt vmcnt(4)
; __device__ __forceinline__ u32x4 pack8(const float* v) { u32x4 w; w.x = pk2(v[0], v[1]); w.y = pk2(v[2], v[3]); w.z = pk2(v[4], v[5]); w.w = pk2(v[6], v[7]); return w; }
; __device__ __forceinline__ void unpack8(u32x4 w, float* v) { v[0] = bflo(w.x); v[1] = bfhi(w.x); v[2] = bflo(w.y); v[3] = bfhi(w.y); v[4] = bflo(w.z); v[5] = bfhi(w.z); v[6] = bflo(w.w); v[7] = bfhi(w.w); }
; __device__ __forceinline__ float siluf_(float x) { return x / (1.f + __expf(-x)); }
; __global__ void __launch_bounds__(NTHR, 2) mk_fwd(Args args) {
;     ...
;                     for (int r = 0; r < 16; ++r) {
;                         u32x4 gn_ = (u32x4){0u, 0u, 0u, 0u}, vn_ = (u32x4){0u, 0u, 0u, 0u};
;                         const int ii = i0 + r;
;                         if (ii != LC - 1 && ii != TB - 1) { gn_ = *(const u32x4*)(up + (size_t)(r + 1) * FF2); vn_ = *(const u32x4*)(up + (size_t)(r + 1) * FF2 + FF); }
;                         float gm[8], gc[8], gn[8], vm[8], vc[8], vn[8], o[8];
;                         unpack8(gp_, gm); unpack8(gc_, gc); unpack8(gn_, gn); unpack8(vp_, vm); unpack8(vc_, vc); unpack8(vn_, vn);
; #pragma unroll
;                         for (int e = 0; e < 8; ++e) {
;                             const float a = wg0[e] * gm[e] + wg1[e] * gc[e] + wg2[e] * gn[e] + bg[e];
;                             const float v = wv0[e] * vm[e] + wv1[e] * vc[e] + wv2[e] * vn[e] + bv[e];
;                             o[e] = siluf_(a) * v;
;                         }
;                         *(u32x4*)(ACT + (size_t)(t0 + r) * FF + j0) = pack8(o);
;                         gp_ = gc_; vp_ = vc_; gc_ = gn_; vc_ = vn_;
	v_mov_b32_e32 v76, v160
	v_mov_b32_e32 v77, v161
	v_mov_b32_e32 v78, v162
	v_mov_b32_e32 v79, v163
	v_lshlrev_b32_e32 v122, 16, v76
	v_mul_f32_e32 v37, 0xbfb8aa3b, v38
	v_exp_f32_e32 v126, v37
	v_mul_f32_e32 v37, 0xbfb8aa3b, v39
	v_exp_f32_e32 v127, v37
	v_and_b32_e32 v123, 0xffff0000, v76
	v_pk_fma_f32 v[106:107], v[64:65], v[122:123], v[106:107]
	v_pk_add_f32 v[126:127], v[126:127], 1.0 op_sel_hi:[1,0]
	s_nop 0
	v_pk_add_f32 v[106:107], v[24:25], v[106:107]
	v_rcp_f32_e32 v37, v127
	s_nop 0
	v_mul_f32_e32 v39, v39, v37
	s_nop 0
	v_pk_mul_f32 v[128:129], v[34:35], v[112:113]
	v_rcp_f32_e32 v37, v126
	s_nop 0
	v_mul_f32_e32 v38, v38, v37
	v_lshlrev_b32_e32 v126, 16, v81
	v_and_b32_e32 v127, 0xffff0000, v81
	v_pk_fma_f32 v[88:89], v[6:7], v[88:89], v[128:129]
	v_pk_mul_f32 v[130:131], v[62:63], v[110:111]
	v_pk_fma_f32 v[88:89], v[50:51], v[126:127], v[88:89]
	v_pk_fma_f32 v[84:85], v[18:19], v[84:85], v[130:131]
	v_pk_add_f32 v[88:89], v[14:15], v[88:89]
	v_pk_mul_f32 v[38:39], v[38:39], v[106:107]
	v_mul_f32_e32 v37, 0xbfb8aa3b, v88
	v_exp_f32_e32 v128, v37
	v_mul_f32_e32 v37, 0xbfb8aa3b, v89
	v_exp_f32_e32 v129, v37
	v_lshlrev_b32_e32 v106, 16, v77
	v_and_b32_e32 v107, 0xffff0000, v77
	v_pk_fma_f32 v[84:85], v[66:67], v[106:107], v[84:85]
	v_pk_add_f32 v[128:129], v[128:129], 1.0 op_sel_hi:[1,0]
	v_pk_add_f32 v[84:85], v[26:27], v[84:85]
	s_nop 0
	v_rcp_f32_e32 v37, v129
	s_nop 0
	v_mul_f32_e32 v89, v89, v37
	v_pk_mul_f32 v[134:135], v[68:69], v[114:115]
	v_rcp_f32_e32 v37, v128
	s_nop 0
	v_mul_f32_e32 v88, v88, v37
	v_pk_mul_f32 v[84:85], v[88:89], v[84:85]
	v_pk_mul_f32 v[88:89], v[52:53], v[116:117]
	v_lshlrev_b32_e32 v130, 16, v82
	v_and_b32_e32 v131, 0xffff0000, v82
	v_pk_fma_f32 v[88:89], v[0:1], v[96:97], v[88:89]
	v_pk_fma_f32 v[108:109], v[20:21], v[108:109], v[134:135]
	v_pk_fma_f32 v[88:89], v[56:57], v[130:131], v[88:89]
	v_lshlrev_b32_e32 v128, 16, v78
	v_pk_add_f32 v[88:89], v[8:9], v[88:89]
	v_and_b32_e32 v129, 0xffff0000, v78
	v_mul_f32_e32 v37, 0xbfb8aa3b, v88
	v_exp_f32_e32 v96, v37
	v_mul_f32_e32 v37, 0xbfb8aa3b, v89
	v_exp_f32_e32 v97, v37
	v_pk_fma_f32 v[108:109], v[72:73], v[128:129], v[108:109]
	v_pk_add_f32 v[96:97], v[96:97], 1.0 op_sel_hi:[1,0]
	s_nop 0
	v_pk_add_f32 v[108:109], v[28:29], v[108:109]
	v_rcp_f32_e32 v37, v97
	s_nop 0
	v_mul_f32_e32 v89, v89, v37
	v_pk_mul_f32 v[136:137], v[70:71], v[118:119]
	v_rcp_f32_e32 v37, v96
	s_nop 0
	v_mul_f32_e32 v88, v88, v37
	v_pk_mul_f32 v[134:135], v[54:55], v[120:121]
	v_pk_mul_f32 v[88:89], v[88:89], v[108:109]
	v_lshlrev_b32_e32 v108, 16, v83
	v_and_b32_e32 v109, 0xffff0000, v83
	v_pk_fma_f32 v[90:91], v[2:3], v[90:91], v[134:135]
	v_pk_fma_f32 v[86:87], v[22:23], v[86:87], v[136:137]
	v_pk_fma_f32 v[90:91], v[58:59], v[108:109], v[90:91]
	v_lshlrev_b32_e32 v96, 16, v79
	v_pk_add_f32 v[90:91], v[10:11], v[90:91]
	v_and_b32_e32 v97, 0xffff0000, v79
	v_mul_f32_e32 v37, 0xbfb8aa3b, v90
	v_exp_f32_e32 v134, v37
	v_mul_f32_e32 v37, 0xbfb8aa3b, v91
	v_exp_f32_e32 v135, v37
	v_pk_fma_f32 v[86:87], v[74:75], v[96:97], v[86:87]
	v_cvt_pk_bf16_f32 v88, v88, v89
	v_pk_add_f32 v[86:87], v[30:31], v[86:87]
	v_pk_add_f32 v[134:135], v[134:135], 1.0 op_sel_hi:[1,0]
	s_nop 0
	s_nop 0
	v_rcp_f32_e32 v37, v135
	s_nop 0
	v_mul_f32_e32 v91, v91, v37
	s_nop 0
	v_rcp_f32_e32 v37, v134
	s_nop 0
	v_mul_f32_e32 v90, v90, v37
	v_pk_mul_f32 v[90:91], v[90:91], v[86:87]
	v_cvt_pk_bf16_f32 v86, v38, v39
	v_add_co_u32_e32 v38, vcc, 0x13f22000, v92
	v_cvt_pk_bf16_f32 v87, v84, v85
	v_cvt_pk_bf16_f32 v89, v90, v91
	v_addc_co_u32_e32 v39, vcc, 0, v93, vcc
	global_store_dwordx4 v[38:39], v[86:89], off offset:3072
	v_mov_b32_e32 v38, v36
	v_mov_b32_e32 v39, v36
	v_mov_b32_e32 v37, v36
	v_mov_b64_e32 v[90:91], v[38:39]
	v_mov_b64_e32 v[86:87], v[38:39]
	v_cmp_ne_u32_e32 vcc, s18, v132
	v_mov_b64_e32 v[88:89], v[36:37]
	v_mov_b64_e32 v[84:85], v[36:37]
	s_and_saveexec_b64 s[0:1], vcc
	s_cbranch_execz .LBB0_90
	v_add_co_u32_e32 v38, vcc, 0x89ab000, v104
	s_nop 1
	v_addc_co_u32_e32 v39, vcc, 0, v105, vcc
	v_add_co_u32_e32 v84, vcc, 0x89ac000, v104
	s_nop 1
	v_addc_co_u32_e32 v85, vcc, 0, v105, vcc
	s_waitcnt vmcnt(4)
	v_mov_b32_e32 v88, v164
	v_mov_b32_e32 v89, v165
	v_mov_b32_e32 v90, v166
	v_mov_b32_e32 v91, v167
	s_nop 0
	s_waitcnt vmcnt(3)
	v_mov_b32_e32 v84, v168
	v_mov_b32_e32 v85, v169
	v_mov_b32_e32 v86, v170
	v_mov_b32_e32 v87, v171
	s_branch .LBB0_90
